# GEMM phases: one static s_setprio 1 for waves 4-7 in the tile prologue (per-phase flips already deleted)
# speedup vs baseline: 1.0355x; 1.0070x over previous
.LBB0_31:
	s_ashr_i32 s0, s76, 31
	s_lshr_b32 s0, s0, 29
	s_add_i32 s0, s76, s0
	s_ashr_i32 s1, s0, 3
	s_and_b32 s0, s0, -8
	s_sub_i32 s0, s76, s0
	s_lshr_b32 s4, s0, 31
	s_or_b32 s4, s4, 0x84
	s_mul_i32 s56, s4, s0
	s_add_i32 s56, s56, s1
	s_mul_hi_i32 s0, s56, 0x2aaaaaab
	s_lshr_b32 s1, s0, 31
	s_ashr_i32 s57, s0, 5
	s_add_i32 s57, s57, s1
	s_lshl_b32 s4, s57, 2
	s_sub_i32 s0, 22, s4
	s_min_u32 s5, s0, 4
	s_mul_i32 s62, s57, 0xc0
	s_sub_i32 s10, s56, s62
	v_cvt_f32_ubyte0_e32 v2, s5
	v_cvt_f32_i32_e32 v0, s10
	v_rcp_iflag_f32_e32 v3, v2
	s_ashr_i32 s0, s10, 30
	v_mov_b32_e32 v142, v206
	v_mul_f32_e32 v3, v0, v3
	v_trunc_f32_e32 v3, v3
	v_fma_f32 v0, -v3, v2, v0
	s_barrier
	s_or_b32 s11, s0, 1
	v_cmp_ge_f32_e64 s[0:1], |v0|, v2
	v_cvt_i32_f32_e32 v3, v3
	v_ashrrev_i32_e32 v0, 31, v142
	v_lshrrev_b32_e32 v0, 26, v0
	v_add_u32_e32 v0, v142, v0
	v_ashrrev_i32_e32 v4, 6, v0
	v_bfe_i32 v0, v142, 27, 1
	v_lshlrev_b32_e32 v147, 4, v142
	v_lshrrev_b32_e32 v0, 22, v0
	v_add_u32_e32 v0, v147, v0
	v_and_b32_e32 v0, 0xfffffc00, v0
	v_sub_u32_e32 v0, v147, v0
	v_lshrrev_b32_e32 v2, 4, v0
	v_bitop3_b32 v2, v2, v0, 32 bitop3:0x6c
	v_ashrrev_i32_e32 v0, 31, v0
	v_lshrrev_b32_e32 v0, 26, v0
	v_add_u32_e32 v0, v2, v0
	v_ashrrev_i32_e32 v5, 6, v0
	v_mul_i32_i24_e32 v6, 64, v5
	s_and_b64 s[0:1], s[0:1], exec
	v_sub_u32_e32 v2, v2, v6
	v_readfirstlane_b32 s1, v3
	v_lshlrev_b32_e32 v3, 3, v4
	v_lshlrev_b32_e32 v0, 5, v4
	v_ashrrev_i16_sdwa v2, v207, sext(v2) dst_sel:DWORD dst_unused:UNUSED_PAD src0_sel:DWORD src1_sel:BYTE_0
	v_and_b32_e32 v3, 0xffff0, v3
	v_and_b32_e32 v0, 32, v0
	v_bfe_i32 v7, v2, 0, 16
	v_add_u32_e32 v0, v0, v7
	v_add_lshl_u32 v2, v5, v3, 12
	v_add_u32_e32 v148, 0x2000, v147
	s_cselect_b32 s0, s11, 0
	v_lshl_add_u32 v0, v0, 1, v2
	v_ashrrev_i32_e32 v2, 31, v148
	s_add_i32 s63, s1, s0
	v_lshrrev_b32_e32 v2, 22, v2
	s_sext_i32_i16 s0, s63
	s_mul_i32 s63, s63, s5
	v_add_u32_e32 v2, v148, v2
	s_sub_i32 s1, s10, s63
	v_ashrrev_i32_e32 v6, 10, v2
	s_sext_i32_i16 s1, s1
	v_mul_i32_i24_e32 v2, 0x400, v6
	s_add_i32 s4, s4, s1
	v_sub_u32_e32 v2, v148, v2
	s_lshl_b32 s4, s4, 8
	v_lshrrev_b32_e32 v3, 4, v2
	v_bitop3_b32 v2, v3, v2, 32 bitop3:0x6c
	s_ashr_i32 s5, s4, 31
	s_lshl_b32 s10, s0, 8
	v_ashrrev_i32_e32 v8, 31, v2
	s_lshl_b64 s[0:1], s[4:5], 12
	v_lshrrev_b32_e32 v8, 26, v8
	s_add_u32 s0, s6, s0
	v_add_u32_e32 v9, v2, v8
	s_addc_u32 s1, s7, s1
	s_ashr_i32 s11, s10, 31
	v_ashrrev_i32_e32 v8, 6, v9
	v_and_b32_e32 v9, 0xc0, v9
	s_lshl_b64 s[12:13], s[10:11], 12
	v_sub_u32_e32 v2, v2, v9
	s_add_u32 s14, s88, s12
	v_lshlrev_b32_e32 v3, 3, v6
	v_lshlrev_b32_e32 v10, 5, v6
	v_ashrrev_i16_sdwa v2, v207, sext(v2) dst_sel:DWORD dst_unused:UNUSED_PAD src0_sel:DWORD src1_sel:BYTE_0
	v_add_u32_e32 v149, 0x10000, v147
	s_addc_u32 s15, s89, s13
	s_or_b32 s16, s4, 0x80
	v_and_b32_e32 v3, 0xffff0, v3
	v_and_b32_e32 v10, 32, v10
	v_bfe_i32 v9, v2, 0, 16
	v_readfirstlane_b32 s5, v149
	v_add_u32_e32 v150, 0x12000, v147
	s_ashr_i32 s17, s16, 31
	v_add_u32_e32 v2, v10, v9
	v_add_lshl_u32 v3, v8, v3, 12
	s_mov_b32 m0, s5
	v_readfirstlane_b32 s5, v150
	s_lshl_b64 s[16:17], s[16:17], 12
	v_lshl_add_u32 v2, v2, 1, v3
	global_load_lds_dwordx4 v0, s[0:1]
	s_mov_b32 m0, s5
	v_readfirstlane_b32 s5, v147
	s_add_u32 s16, s6, s16
	global_load_lds_dwordx4 v2, s[0:1]
	s_mov_b32 m0, s5
	v_readfirstlane_b32 s5, v148
	s_addc_u32 s17, s7, s17
	v_add_u32_e32 v152, 0x14000, v147
	s_or_b32 s52, s10, 0x80
	global_load_lds_dwordx4 v0, s[14:15]
	s_mov_b32 m0, s5
	v_readfirstlane_b32 s5, v152
	v_add_u32_e32 v153, 0x16000, v147
	s_ashr_i32 s53, s52, 31
	global_load_lds_dwordx4 v2, s[14:15]
	s_mov_b32 m0, s5
	v_readfirstlane_b32 s5, v153
	s_lshl_b64 s[52:53], s[52:53], 12
	v_add_u32_e32 v154, 0x4000, v147
	global_load_lds_dwordx4 v0, s[16:17]
	s_mov_b32 m0, s5
	s_add_u32 s72, s88, s52
	v_readfirstlane_b32 s5, v154
	v_add_u32_e32 v155, 0x6000, v147
	global_load_lds_dwordx4 v2, s[16:17]
	s_addc_u32 s73, s89, s53
	s_mov_b32 m0, s5
	v_readfirstlane_b32 s5, v155
	global_load_lds_dwordx4 v0, s[72:73]
	s_mov_b32 m0, s5
	v_ashrrev_i32_e32 v143, 8, v142
	global_load_lds_dwordx4 v2, s[72:73]
	v_cmp_eq_u32_e32 vcc, 1, v143
	s_and_saveexec_b64 s[52:53], vcc
	s_cbranch_execz .LBB0_33
	s_barrier
	s_setprio 1

.LBB0_82:
	s_ashr_i32 s0, s56, 31
	s_lshr_b32 s0, s0, 29
	s_add_i32 s0, s56, s0
	s_ashr_i32 s1, s0, 3
	s_and_b32 s0, s0, -8
	s_sub_i32 s0, s56, s0
	s_lshr_b32 s6, s0, 31
	s_or_b32 s6, s6, 0x84
	s_mul_i32 s57, s6, s0
	s_add_i32 s57, s57, s1
	s_mul_hi_i32 s0, s57, 0x2aaaaaab
	s_lshr_b32 s1, s0, 31
	s_ashr_i32 s62, s0, 5
	s_add_i32 s62, s62, s1
	s_lshl_b32 s6, s62, 2
	s_sub_i32 s0, 22, s6
	s_min_u32 s7, s0, 4
	s_mul_i32 s63, s62, 0xc0
	s_sub_i32 s8, s57, s63
	v_cvt_f32_ubyte0_e32 v2, s7
	v_cvt_f32_i32_e32 v0, s8
	v_rcp_iflag_f32_e32 v3, v2
	s_ashr_i32 s0, s8, 30
	v_mov_b32_e32 v142, v206
	v_mul_f32_e32 v3, v0, v3
	v_trunc_f32_e32 v3, v3
	v_fma_f32 v0, -v3, v2, v0
	s_barrier
	s_or_b32 s9, s0, 1
	v_cmp_ge_f32_e64 s[0:1], |v0|, v2
	v_cvt_i32_f32_e32 v3, v3
	v_ashrrev_i32_e32 v0, 31, v142
	v_lshrrev_b32_e32 v0, 26, v0
	v_add_u32_e32 v0, v142, v0
	v_ashrrev_i32_e32 v4, 6, v0
	v_bfe_i32 v0, v142, 27, 1
	v_lshlrev_b32_e32 v147, 4, v142
	v_lshrrev_b32_e32 v0, 22, v0
	v_add_u32_e32 v0, v147, v0
	v_and_b32_e32 v0, 0xfffffc00, v0
	v_sub_u32_e32 v0, v147, v0
	v_lshrrev_b32_e32 v2, 4, v0
	v_bitop3_b32 v2, v2, v0, 32 bitop3:0x6c
	v_ashrrev_i32_e32 v0, 31, v0
	v_lshrrev_b32_e32 v0, 26, v0
	v_add_u32_e32 v0, v2, v0
	v_ashrrev_i32_e32 v5, 6, v0
	v_mul_i32_i24_e32 v6, 64, v5
	s_and_b64 s[0:1], s[0:1], exec
	v_sub_u32_e32 v2, v2, v6
	v_readfirstlane_b32 s1, v3
	v_lshlrev_b32_e32 v3, 3, v4
	v_lshlrev_b32_e32 v0, 5, v4
	v_ashrrev_i16_sdwa v2, v207, sext(v2) dst_sel:DWORD dst_unused:UNUSED_PAD src0_sel:DWORD src1_sel:BYTE_0
	v_and_b32_e32 v3, 0xffff0, v3
	v_and_b32_e32 v0, 32, v0
	v_bfe_i32 v7, v2, 0, 16
	v_add_u32_e32 v0, v0, v7
	v_add_lshl_u32 v2, v5, v3, 12
	v_add_u32_e32 v148, 0x2000, v147
	s_cselect_b32 s0, s9, 0
	v_lshl_add_u32 v0, v0, 1, v2
	v_ashrrev_i32_e32 v2, 31, v148
	s_add_i32 s64, s1, s0
	v_lshrrev_b32_e32 v2, 22, v2
	s_sext_i32_i16 s0, s64
	s_mul_i32 s64, s64, s7
	v_add_u32_e32 v2, v148, v2
	s_sub_i32 s1, s8, s64
	v_ashrrev_i32_e32 v6, 10, v2
	s_sext_i32_i16 s1, s1
	v_mul_i32_i24_e32 v2, 0x400, v6
	s_add_i32 s6, s6, s1
	v_sub_u32_e32 v2, v148, v2
	s_lshl_b32 s6, s6, 8
	v_lshrrev_b32_e32 v3, 4, v2
	v_bitop3_b32 v2, v3, v2, 32 bitop3:0x6c
	s_ashr_i32 s7, s6, 31
	s_lshl_b32 s8, s0, 8
	v_ashrrev_i32_e32 v8, 31, v2
	s_lshl_b64 s[0:1], s[6:7], 12
	v_lshrrev_b32_e32 v8, 26, v8
	s_add_u32 s0, s4, s0
	v_add_u32_e32 v9, v2, v8
	s_addc_u32 s1, s5, s1
	s_ashr_i32 s9, s8, 31
	v_ashrrev_i32_e32 v8, 6, v9
	v_and_b32_e32 v9, 0xc0, v9
	s_lshl_b64 s[10:11], s[8:9], 12
	v_sub_u32_e32 v2, v2, v9
	s_add_u32 s12, s88, s10
	v_lshlrev_b32_e32 v3, 3, v6
	v_lshlrev_b32_e32 v10, 5, v6
	v_ashrrev_i16_sdwa v2, v207, sext(v2) dst_sel:DWORD dst_unused:UNUSED_PAD src0_sel:DWORD src1_sel:BYTE_0
	v_add_u32_e32 v149, 0x10000, v147
	s_addc_u32 s13, s89, s11
	s_or_b32 s14, s6, 0x80
	v_and_b32_e32 v3, 0xffff0, v3
	v_and_b32_e32 v10, 32, v10
	v_bfe_i32 v9, v2, 0, 16
	v_readfirstlane_b32 s7, v149
	v_add_u32_e32 v150, 0x12000, v147
	s_ashr_i32 s15, s14, 31
	v_add_u32_e32 v2, v10, v9
	v_add_lshl_u32 v3, v8, v3, 12
	s_mov_b32 m0, s7
	v_readfirstlane_b32 s7, v150
	s_lshl_b64 s[14:15], s[14:15], 12
	v_lshl_add_u32 v2, v2, 1, v3
	global_load_lds_dwordx4 v0, s[0:1]
	s_mov_b32 m0, s7
	v_readfirstlane_b32 s7, v147
	s_add_u32 s14, s4, s14
	global_load_lds_dwordx4 v2, s[0:1]
	s_mov_b32 m0, s7
	v_readfirstlane_b32 s7, v148
	s_addc_u32 s15, s5, s15
	v_add_u32_e32 v152, 0x14000, v147
	s_or_b32 s16, s8, 0x80
	global_load_lds_dwordx4 v0, s[12:13]
	s_mov_b32 m0, s7
	v_readfirstlane_b32 s7, v152
	v_add_u32_e32 v153, 0x16000, v147
	s_ashr_i32 s17, s16, 31
	global_load_lds_dwordx4 v2, s[12:13]
	s_mov_b32 m0, s7
	v_readfirstlane_b32 s7, v153
	s_lshl_b64 s[16:17], s[16:17], 12
	v_add_u32_e32 v154, 0x4000, v147
	global_load_lds_dwordx4 v0, s[14:15]
	s_mov_b32 m0, s7
	s_add_u32 s16, s88, s16
	v_readfirstlane_b32 s7, v154
	v_add_u32_e32 v155, 0x6000, v147
	global_load_lds_dwordx4 v2, s[14:15]
	s_addc_u32 s17, s89, s17
	s_mov_b32 m0, s7
	v_readfirstlane_b32 s7, v155
	global_load_lds_dwordx4 v0, s[16:17]
	s_mov_b32 m0, s7
	v_ashrrev_i32_e32 v143, 8, v142
	global_load_lds_dwordx4 v2, s[16:17]
	v_cmp_eq_u32_e32 vcc, 1, v143
	s_and_saveexec_b64 s[52:53], vcc
	s_cbranch_execz .LBB0_84
	s_barrier
	s_setprio 1

.LBB0_105:
	s_ashr_i32 s0, s53, 1
	s_addk_i32 s0, 0x100
	s_ashr_i32 s1, s0, 31
	s_lshr_b32 s1, s1, 29
	s_add_i32 s1, s0, s1
	s_ashr_i32 s4, s1, 3
	s_and_b32 s1, s1, -8
	s_sub_i32 s0, s0, s1
	s_lshr_b32 s1, s0, 31
	s_or_b32 s1, s1, 48
	s_mul_i32 s56, s1, s0
	s_add_i32 s56, s56, s4
	s_mul_hi_i32 s0, s56, 0x2aaaaaab
	s_lshr_b32 s1, s0, 31
	s_ashr_i32 s76, s0, 5
	s_add_i32 s76, s76, s1
	s_lshl_b32 s4, s76, 2
	s_sub_i32 s0, 8, s4
	s_min_u32 s5, s0, 4
	s_mul_i32 s77, s76, 0xc0
	s_sub_i32 s8, s56, s77
	v_cvt_f32_ubyte0_e32 v2, s5
	v_cvt_f32_i32_e32 v0, s8
	v_rcp_iflag_f32_e32 v3, v2
	s_ashr_i32 s0, s8, 30
	s_waitcnt vmcnt(0)
	v_mov_b32_e32 v82, v206
	v_mul_f32_e32 v3, v0, v3
	v_trunc_f32_e32 v3, v3
	v_fma_f32 v0, -v3, v2, v0
	s_barrier
	s_or_b32 s9, s0, 1
	v_cmp_ge_f32_e64 s[0:1], |v0|, v2
	v_cvt_i32_f32_e32 v3, v3
	v_ashrrev_i32_e32 v0, 31, v82
	v_lshrrev_b32_e32 v0, 26, v0
	v_add_u32_e32 v0, v82, v0
	v_ashrrev_i32_e32 v4, 6, v0
	v_bfe_i32 v0, v82, 27, 1
	v_lshlrev_b32_e32 v87, 4, v82
	v_lshrrev_b32_e32 v0, 22, v0
	v_add_u32_e32 v0, v87, v0
	v_and_b32_e32 v0, 0xfffffc00, v0
	v_sub_u32_e32 v0, v87, v0
	v_lshrrev_b32_e32 v2, 4, v0
	v_bitop3_b32 v2, v2, v0, 32 bitop3:0x6c
	v_ashrrev_i32_e32 v0, 31, v0
	s_and_b64 s[0:1], s[0:1], exec
	v_lshrrev_b32_e32 v0, 26, v0
	v_readfirstlane_b32 s1, v3
	v_lshlrev_b32_e32 v3, 3, v4
	v_add_u32_e32 v0, v2, v0
	v_and_b32_e32 v3, 0xffff0, v3
	v_ashrrev_i32_e32 v5, 6, v0
	v_add_u32_e32 v0, v5, v3
	v_lshlrev_b32_e32 v3, 5, v4
	v_and_b32_e32 v6, 32, v3
	v_mul_i32_i24_e32 v3, 64, v5
	v_sub_u32_e32 v2, v2, v3
	v_ashrrev_i16_sdwa v2, v207, sext(v2) dst_sel:DWORD dst_unused:UNUSED_PAD src0_sel:DWORD src1_sel:BYTE_0
	v_add_u32_e32 v88, 0x2000, v87
	s_cselect_b32 s0, s9, 0
	v_bfe_i32 v8, v2, 0, 16
	v_ashrrev_i32_e32 v2, 31, v88
	s_add_i32 s54, s1, s0
	v_lshrrev_b32_e32 v2, 22, v2
	s_sext_i32_i16 s0, s54
	s_mul_i32 s54, s54, s5
	v_add_u32_e32 v2, v88, v2
	s_sub_i32 s1, s8, s54
	v_ashrrev_i32_e32 v7, 10, v2
	s_sext_i32_i16 s1, s1
	v_mul_i32_i24_e32 v2, 0x400, v7
	s_add_i32 s4, s4, s1
	s_lshl_b32 s1, s53, 7
	v_sub_u32_e32 v2, v88, v2
	s_lshl_b32 s8, s0, 8
	s_lshl_b32 s0, s4, 8
	s_and_b32 s1, s1, 0x80
	v_lshrrev_b32_e32 v3, 4, v2
	s_or_b32 s4, s0, s1
	v_bitop3_b32 v2, v3, v2, 32 bitop3:0x6c
	v_ashrrev_i32_e32 v9, 31, v2
	s_ashr_i32 s5, s4, 31
	v_lshrrev_b32_e32 v9, 26, v9
	s_lshl_b64 s[0:1], s[4:5], 12
	v_add_u32_e32 v11, v2, v9
	s_add_u32 s0, s57, s0
	v_lshlrev_b32_e32 v3, 3, v7
	v_ashrrev_i32_e32 v9, 6, v11
	v_and_b32_e32 v11, 0xc0, v11
	s_addc_u32 s1, s63, s1
	s_ashr_i32 s9, s8, 31
	v_readlane_b32 s36, v253, 33
	v_and_b32_e32 v3, 0xffff0, v3
	v_lshlrev_b32_e32 v10, 5, v7
	v_sub_u32_e32 v2, v2, v11
	v_add_u32_e32 v89, 0x10000, v87
	s_lshl_b64 s[10:11], s[8:9], 12
	v_readlane_b32 s48, v253, 45
	v_lshl_or_b32 v0, v0, 11, v6
	v_add_u32_e32 v3, v9, v3
	v_and_b32_e32 v10, 32, v10
	v_ashrrev_i16_sdwa v2, v207, sext(v2) dst_sel:DWORD dst_unused:UNUSED_PAD src0_sel:DWORD src1_sel:BYTE_0
	v_readfirstlane_b32 s5, v89
	v_add_u32_e32 v90, 0x12000, v87
	v_readlane_b32 s49, v253, 46
	s_add_u32 s12, s48, s10
	v_add_lshl_u32 v0, v0, v8, 1
	v_bfe_i32 v11, v2, 0, 16
	v_lshl_or_b32 v2, v3, 11, v10
	s_mov_b32 m0, s5
	v_readfirstlane_b32 s5, v90
	s_addc_u32 s13, s49, s11
	v_add_lshl_u32 v2, v2, v11, 1
	global_load_lds_dwordx4 v0, s[0:1]
	s_mov_b32 m0, s5
	v_readfirstlane_b32 s5, v87
	s_add_u32 s14, s0, 0x80000
	global_load_lds_dwordx4 v2, s[0:1]
	s_mov_b32 m0, s5
	v_readfirstlane_b32 s5, v88
	s_addc_u32 s15, s1, 0
	v_add_u32_e32 v91, 0x14000, v87
	s_or_b32 s16, s8, 0x80
	global_load_lds_dwordx4 v0, s[12:13]
	s_mov_b32 m0, s5
	v_readfirstlane_b32 s5, v91
	v_add_u32_e32 v92, 0x16000, v87
	s_ashr_i32 s17, s16, 31
	global_load_lds_dwordx4 v2, s[12:13]
	s_mov_b32 m0, s5
	v_readfirstlane_b32 s5, v92
	s_lshl_b64 s[16:17], s[16:17], 12
	v_add_u32_e32 v93, 0x4000, v87
	global_load_lds_dwordx4 v0, s[14:15]
	s_mov_b32 m0, s5
	s_add_u32 s16, s48, s16
	v_readfirstlane_b32 s5, v93
	v_add_u32_e32 v94, 0x6000, v87
	global_load_lds_dwordx4 v2, s[14:15]
	s_addc_u32 s17, s49, s17
	s_mov_b32 m0, s5
	v_readfirstlane_b32 s5, v94
	global_load_lds_dwordx4 v0, s[16:17]
	s_mov_b32 m0, s5
	v_ashrrev_i32_e32 v83, 8, v82
	global_load_lds_dwordx4 v2, s[16:17]
	v_cmp_eq_u32_e32 vcc, 1, v83
	v_readlane_b32 s37, v253, 34
	v_readlane_b32 s38, v253, 35
	v_readlane_b32 s39, v253, 36
	v_readlane_b32 s40, v253, 37
	v_readlane_b32 s41, v253, 38
	v_readlane_b32 s42, v253, 39
	v_readlane_b32 s43, v253, 40
	v_readlane_b32 s44, v253, 41
	v_readlane_b32 s45, v253, 42
	v_readlane_b32 s46, v253, 43
	v_readlane_b32 s47, v253, 44
	v_readlane_b32 s50, v253, 47
	v_readlane_b32 s51, v253, 48
	s_and_saveexec_b64 s[72:73], vcc
	s_cbranch_execz .LBB0_107
	s_barrier
	s_setprio 1

.LBB0_177:
	v_mov_b32_e32 v142, v206
	s_barrier
	s_ashr_i32 s0, s56, 31
	v_ashrrev_i32_e32 v0, 31, v142
	v_lshrrev_b32_e32 v0, 26, v0
	s_lshr_b32 s0, s0, 29
	v_add_u32_e32 v0, v142, v0
	s_add_i32 s0, s56, s0
	v_ashrrev_i32_e32 v4, 6, v0
	v_bfe_i32 v0, v142, 27, 1
	s_ashr_i32 s1, s0, 3
	s_and_b32 s0, s0, -8
	v_lshlrev_b32_e32 v147, 4, v142
	v_lshrrev_b32_e32 v0, 22, v0
	s_sub_i32 s0, s56, s0
	v_add_u32_e32 v0, v147, v0
	s_lshr_b32 s8, s0, 31
	v_and_b32_e32 v0, 0xfffffc00, v0
	s_or_b32 s8, s8, 48
	v_sub_u32_e32 v0, v147, v0
	s_mul_i32 s0, s8, s0
	v_lshrrev_b32_e32 v2, 4, v0
	s_add_i32 s0, s0, s1
	v_bitop3_b32 v2, v2, v0, 32 bitop3:0x6c
	v_ashrrev_i32_e32 v0, 31, v0
	s_mul_hi_i32 s1, s0, 0x2aaaaaab
	v_lshrrev_b32_e32 v0, 26, v0
	s_lshr_b32 s8, s1, 31
	s_ashr_i32 s1, s1, 5
	v_lshlrev_b32_e32 v3, 3, v4
	v_add_u32_e32 v0, v2, v0
	s_add_i32 s1, s1, s8
	v_and_b32_e32 v3, 0xffff0, v3
	v_ashrrev_i32_e32 v5, 6, v0
	s_mul_i32 s8, s1, 0xc0
	v_add_u32_e32 v0, v5, v3
	v_lshlrev_b32_e32 v3, 5, v4
	s_sub_i32 s0, s0, s8
	v_and_b32_e32 v6, 32, v3
	v_mul_i32_i24_e32 v3, 64, v5
	s_sext_i32_i16 s8, s0
	v_sub_u32_e32 v2, v2, v3
	s_bfe_u32 s8, s8, 0x2001d
	v_ashrrev_i16_sdwa v2, v207, sext(v2) dst_sel:DWORD dst_unused:UNUSED_PAD src0_sel:DWORD src1_sel:BYTE_0
	v_add_u32_e32 v148, 0x2000, v147
	s_add_i32 s8, s0, s8
	v_bfe_i32 v8, v2, 0, 16
	v_ashrrev_i32_e32 v2, 31, v148
	s_sext_i32_i16 s9, s8
	s_and_b32 s8, s8, 0xfffc
	v_lshrrev_b32_e32 v2, 22, v2
	s_sub_i32 s0, s0, s8
	v_add_u32_e32 v2, v148, v2
	s_sext_i32_i16 s0, s0
	v_ashrrev_i32_e32 v7, 10, v2
	s_lshl_b32 s8, s9, 6
	s_lshl_b32 s1, s1, 10
	s_lshl_b32 s0, s0, 8
	v_mul_i32_i24_e32 v2, 0x400, v7
	s_and_b32 s10, s8, 0xffffff00
	s_add_i32 s8, s0, s1
	v_sub_u32_e32 v2, v148, v2
	v_lshrrev_b32_e32 v3, 4, v2
	s_ashr_i32 s9, s8, 31
	v_bitop3_b32 v2, v3, v2, 32 bitop3:0x6c
	s_lshl_b64 s[12:13], s[8:9], 12
	v_ashrrev_i32_e32 v9, 31, v2
	s_add_u32 s0, s57, s12
	v_lshrrev_b32_e32 v9, 26, v9
	s_addc_u32 s1, s63, s13
	s_ashr_i32 s11, s10, 31
	v_readlane_b32 s36, v253, 33
	v_add_u32_e32 v11, v2, v9
	s_lshl_b64 s[14:15], s[10:11], 12
	v_readlane_b32 s48, v253, 45
	v_lshlrev_b32_e32 v3, 3, v7
	v_ashrrev_i32_e32 v9, 6, v11
	v_and_b32_e32 v11, 0xc0, v11
	v_readlane_b32 s49, v253, 46
	s_add_u32 s16, s48, s14
	v_and_b32_e32 v3, 0xffff0, v3
	v_lshlrev_b32_e32 v10, 5, v7
	v_sub_u32_e32 v2, v2, v11
	v_add_u32_e32 v149, 0x10000, v147
	s_addc_u32 s17, s49, s15
	s_or_b32 s52, s8, 0x80
	v_lshl_or_b32 v0, v0, 11, v6
	v_add_u32_e32 v3, v9, v3
	v_and_b32_e32 v10, 32, v10
	v_ashrrev_i16_sdwa v2, v207, sext(v2) dst_sel:DWORD dst_unused:UNUSED_PAD src0_sel:DWORD src1_sel:BYTE_0
	v_readfirstlane_b32 s9, v149
	v_add_u32_e32 v150, 0x12000, v147
	s_ashr_i32 s53, s52, 31
	v_add_lshl_u32 v0, v0, v8, 1
	v_bfe_i32 v11, v2, 0, 16
	v_lshl_or_b32 v2, v3, 11, v10
	s_mov_b32 m0, s9
	v_readfirstlane_b32 s9, v150
	s_lshl_b64 s[52:53], s[52:53], 12
	v_add_lshl_u32 v2, v2, v11, 1
	global_load_lds_dwordx4 v0, s[0:1]
	s_mov_b32 m0, s9
	v_readfirstlane_b32 s9, v147
	s_add_u32 s72, s57, s52
	global_load_lds_dwordx4 v2, s[0:1]
	s_mov_b32 m0, s9
	v_readfirstlane_b32 s9, v148
	s_addc_u32 s73, s63, s53
	v_add_u32_e32 v152, 0x14000, v147
	s_or_b32 s52, s10, 0x80
	global_load_lds_dwordx4 v0, s[16:17]
	s_mov_b32 m0, s9
	v_readfirstlane_b32 s9, v152
	v_add_u32_e32 v153, 0x16000, v147
	s_ashr_i32 s53, s52, 31
	global_load_lds_dwordx4 v2, s[16:17]
	s_mov_b32 m0, s9
	v_readfirstlane_b32 s9, v153
	s_lshl_b64 s[52:53], s[52:53], 12
	v_add_u32_e32 v154, 0x4000, v147
	global_load_lds_dwordx4 v0, s[72:73]
	s_mov_b32 m0, s9
	s_add_u32 s76, s48, s52
	v_readfirstlane_b32 s9, v154
	v_add_u32_e32 v155, 0x6000, v147
	global_load_lds_dwordx4 v2, s[72:73]
	s_addc_u32 s77, s49, s53
	s_mov_b32 m0, s9
	v_readfirstlane_b32 s9, v155
	global_load_lds_dwordx4 v0, s[76:77]
	s_mov_b32 m0, s9
	v_ashrrev_i32_e32 v143, 8, v142
	global_load_lds_dwordx4 v2, s[76:77]
	v_cmp_eq_u32_e32 vcc, 1, v143
	v_readlane_b32 s37, v253, 34
	v_readlane_b32 s38, v253, 35
	v_readlane_b32 s39, v253, 36
	v_readlane_b32 s40, v253, 37
	v_readlane_b32 s41, v253, 38
	v_readlane_b32 s42, v253, 39
	v_readlane_b32 s43, v253, 40
	v_readlane_b32 s44, v253, 41
	v_readlane_b32 s45, v253, 42
	v_readlane_b32 s46, v253, 43
	v_readlane_b32 s47, v253, 44
	v_readlane_b32 s50, v253, 47
	v_readlane_b32 s51, v253, 48
	s_and_saveexec_b64 s[52:53], vcc
	s_cbranch_execz .LBB0_179
	s_barrier
	s_setprio 1

.LBB0_675:
	s_ashr_i32 s0, s56, 31
	s_lshr_b32 s0, s0, 29
	s_add_i32 s0, s56, s0
	s_ashr_i32 s1, s0, 3
	s_and_b32 s0, s0, -8
	s_sub_i32 s0, s56, s0
	s_lshr_b32 s4, s0, 31
	s_or_b32 s4, s4, 0x54
	s_mul_i32 s57, s4, s0
	s_add_i32 s57, s57, s1
	s_mul_hi_i32 s0, s57, 0x2aaaaaab
	s_lshr_b32 s1, s0, 31
	s_ashr_i32 s62, s0, 5
	s_add_i32 s62, s62, s1
	s_lshl_b32 s4, s62, 2
	s_sub_i32 s0, 14, s4
	s_min_u32 s5, s0, 4
	s_mul_i32 s63, s62, 0xc0
	s_sub_i32 s6, s57, s63
	v_cvt_f32_ubyte0_e32 v2, s5
	v_cvt_f32_i32_e32 v0, s6
	v_rcp_iflag_f32_e32 v3, v2
	s_ashr_i32 s0, s6, 30
	v_mov_b32_e32 v142, v206
	s_waitcnt lgkmcnt(0)
	v_mul_f32_e32 v3, v0, v3
	v_trunc_f32_e32 v3, v3
	v_fma_f32 v0, -v3, v2, v0
	s_barrier
	s_or_b32 s7, s0, 1
	v_cmp_ge_f32_e64 s[0:1], |v0|, v2
	v_cvt_i32_f32_e32 v3, v3
	v_ashrrev_i32_e32 v0, 31, v142
	v_lshrrev_b32_e32 v0, 26, v0
	v_add_u32_e32 v0, v142, v0
	v_ashrrev_i32_e32 v4, 6, v0
	v_bfe_i32 v0, v142, 27, 1
	v_lshlrev_b32_e32 v147, 4, v142
	v_lshrrev_b32_e32 v0, 22, v0
	v_add_u32_e32 v0, v147, v0
	v_and_b32_e32 v0, 0xfffffc00, v0
	v_sub_u32_e32 v0, v147, v0
	v_lshrrev_b32_e32 v2, 4, v0
	v_bitop3_b32 v2, v2, v0, 32 bitop3:0x6c
	v_ashrrev_i32_e32 v0, 31, v0
	v_lshrrev_b32_e32 v0, 26, v0
	v_add_u32_e32 v0, v2, v0
	v_ashrrev_i32_e32 v5, 6, v0
	v_mul_i32_i24_e32 v6, 64, v5
	s_and_b64 s[0:1], s[0:1], exec
	v_sub_u32_e32 v2, v2, v6
	v_readfirstlane_b32 s1, v3
	v_lshlrev_b32_e32 v3, 3, v4
	v_lshlrev_b32_e32 v0, 5, v4
	v_ashrrev_i16_sdwa v2, v207, sext(v2) dst_sel:DWORD dst_unused:UNUSED_PAD src0_sel:DWORD src1_sel:BYTE_0
	v_and_b32_e32 v3, 0xffff0, v3
	v_and_b32_e32 v0, 32, v0
	v_bfe_i32 v7, v2, 0, 16
	v_add_u32_e32 v0, v0, v7
	v_add_lshl_u32 v2, v5, v3, 12
	v_add_u32_e32 v148, 0x2000, v147
	s_cselect_b32 s0, s7, 0
	v_lshl_add_u32 v0, v0, 1, v2
	v_ashrrev_i32_e32 v2, 31, v148
	s_add_i32 s64, s1, s0
	v_lshrrev_b32_e32 v2, 22, v2
	s_sext_i32_i16 s0, s64
	s_mul_i32 s64, s64, s5
	v_add_u32_e32 v2, v148, v2
	s_sub_i32 s1, s6, s64
	v_ashrrev_i32_e32 v6, 10, v2
	s_sext_i32_i16 s1, s1
	v_mul_i32_i24_e32 v2, 0x400, v6
	s_add_i32 s4, s4, s1
	v_sub_u32_e32 v2, v148, v2
	s_lshl_b32 s4, s4, 8
	v_lshrrev_b32_e32 v3, 4, v2
	v_bitop3_b32 v2, v3, v2, 32 bitop3:0x6c
	s_ashr_i32 s5, s4, 31
	s_lshl_b32 s6, s0, 8
	v_ashrrev_i32_e32 v8, 31, v2
	s_lshl_b64 s[0:1], s[4:5], 12
	v_lshrrev_b32_e32 v8, 26, v8
	s_add_u32 s0, s52, s0
	v_add_u32_e32 v9, v2, v8
	s_addc_u32 s1, s53, s1
	s_ashr_i32 s7, s6, 31
	v_ashrrev_i32_e32 v8, 6, v9
	v_and_b32_e32 v9, 0xc0, v9
	s_lshl_b64 s[8:9], s[6:7], 12
	v_sub_u32_e32 v2, v2, v9
	s_add_u32 s10, s88, s8
	v_lshlrev_b32_e32 v3, 3, v6
	v_lshlrev_b32_e32 v10, 5, v6
	v_ashrrev_i16_sdwa v2, v207, sext(v2) dst_sel:DWORD dst_unused:UNUSED_PAD src0_sel:DWORD src1_sel:BYTE_0
	v_add_u32_e32 v149, 0x10000, v147
	s_addc_u32 s11, s89, s9
	s_or_b32 s12, s4, 0x80
	v_and_b32_e32 v3, 0xffff0, v3
	v_and_b32_e32 v10, 32, v10
	v_bfe_i32 v9, v2, 0, 16
	v_readfirstlane_b32 s5, v149
	v_add_u32_e32 v150, 0x12000, v147
	s_ashr_i32 s13, s12, 31
	v_add_u32_e32 v2, v10, v9
	v_add_lshl_u32 v3, v8, v3, 12
	s_mov_b32 m0, s5
	v_readfirstlane_b32 s5, v150
	s_lshl_b64 s[12:13], s[12:13], 12
	v_lshl_add_u32 v2, v2, 1, v3
	global_load_lds_dwordx4 v0, s[0:1]
	s_mov_b32 m0, s5
	v_readfirstlane_b32 s5, v147
	s_add_u32 s12, s52, s12
	global_load_lds_dwordx4 v2, s[0:1]
	s_mov_b32 m0, s5
	v_readfirstlane_b32 s5, v148
	s_addc_u32 s13, s53, s13
	v_add_u32_e32 v152, 0x14000, v147
	s_or_b32 s14, s6, 0x80
	global_load_lds_dwordx4 v0, s[10:11]
	s_mov_b32 m0, s5
	v_readfirstlane_b32 s5, v152
	v_add_u32_e32 v153, 0x16000, v147
	s_ashr_i32 s15, s14, 31
	global_load_lds_dwordx4 v2, s[10:11]
	s_mov_b32 m0, s5
	v_readfirstlane_b32 s5, v153
	s_lshl_b64 s[14:15], s[14:15], 12
	v_add_u32_e32 v154, 0x4000, v147
	global_load_lds_dwordx4 v0, s[12:13]
	s_mov_b32 m0, s5
	s_add_u32 s14, s88, s14
	v_readfirstlane_b32 s5, v154
	v_add_u32_e32 v155, 0x6000, v147
	global_load_lds_dwordx4 v2, s[12:13]
	s_addc_u32 s15, s89, s15
	s_mov_b32 m0, s5
	v_readfirstlane_b32 s5, v155
	global_load_lds_dwordx4 v0, s[14:15]
	s_mov_b32 m0, s5
	v_ashrrev_i32_e32 v143, 8, v142
	global_load_lds_dwordx4 v2, s[14:15]
	v_cmp_eq_u32_e32 vcc, 1, v143
	s_and_saveexec_b64 s[16:17], vcc
	s_cbranch_execz .LBB0_677
	s_barrier
	s_setprio 1

.LBB0_686:
	s_ashr_i32 s0, s53, 1
	s_addk_i32 s0, 0x100
	s_ashr_i32 s1, s0, 31
	s_lshr_b32 s1, s1, 29
	s_add_i32 s1, s0, s1
	s_ashr_i32 s8, s1, 3
	s_and_b32 s1, s1, -8
	s_sub_i32 s0, s0, s1
	s_lshr_b32 s1, s0, 31
	s_or_b32 s1, s1, 48
	s_mul_i32 s62, s1, s0
	s_add_i32 s62, s62, s8
	s_mul_hi_i32 s0, s62, 0x2aaaaaab
	s_lshr_b32 s1, s0, 31
	s_ashr_i32 s63, s0, 5
	s_add_i32 s63, s63, s1
	s_lshl_b32 s8, s63, 2
	s_sub_i32 s0, 8, s8
	s_min_u32 s9, s0, 4
	s_mul_i32 s64, s63, 0xc0
	s_sub_i32 s10, s62, s64
	v_cvt_f32_ubyte0_e32 v2, s9
	v_cvt_f32_i32_e32 v0, s10
	v_rcp_iflag_f32_e32 v3, v2
	s_ashr_i32 s0, s10, 30
	v_mov_b32_e32 v80, v206
	s_waitcnt vmcnt(0) lgkmcnt(0)
	v_mul_f32_e32 v3, v0, v3
	v_trunc_f32_e32 v3, v3
	v_fma_f32 v0, -v3, v2, v0
	s_barrier
	s_or_b32 s11, s0, 1
	v_cmp_ge_f32_e64 s[0:1], |v0|, v2
	v_cvt_i32_f32_e32 v3, v3
	v_ashrrev_i32_e32 v0, 31, v80
	v_lshrrev_b32_e32 v0, 26, v0
	v_add_u32_e32 v0, v80, v0
	v_ashrrev_i32_e32 v2, 6, v0
	v_bfe_i32 v0, v80, 27, 1
	v_lshlrev_b32_e32 v85, 4, v80
	v_lshrrev_b32_e32 v0, 22, v0
	v_add_u32_e32 v0, v85, v0
	v_and_b32_e32 v0, 0xfffffc00, v0
	s_and_b64 s[0:1], s[0:1], exec
	v_sub_u32_e32 v0, v85, v0
	v_readfirstlane_b32 s1, v3
	v_lshrrev_b32_e32 v3, 4, v0
	v_bitop3_b32 v5, v3, v0, 32 bitop3:0x6c
	v_ashrrev_i32_e32 v0, 31, v0
	v_lshrrev_b32_e32 v0, 26, v0
	v_add_u32_e32 v0, v5, v0
	v_ashrrev_i32_e32 v4, 6, v0
	v_mul_i32_i24_e32 v6, 64, v4
	v_add_u32_e32 v86, 0x2000, v85
	v_sub_u32_e32 v5, v5, v6
	v_ashrrev_i32_e32 v6, 31, v86
	v_lshrrev_b32_e32 v6, 22, v6
	v_add_u32_e32 v6, v86, v6
	v_ashrrev_i32_e32 v6, 10, v6
	s_cselect_b32 s0, s11, 0
	v_mul_i32_i24_e32 v7, 0x400, v6
	s_add_i32 s54, s1, s0
	v_sub_u32_e32 v7, v86, v7
	s_sext_i32_i16 s11, s54
	s_mul_i32 s54, s54, s9
	v_lshrrev_b32_e32 v8, 4, v7
	s_sub_i32 s0, s10, s54
	v_bitop3_b32 v9, v8, v7, 32 bitop3:0x6c
	s_sext_i32_i16 s0, s0
	v_ashrrev_i32_e32 v8, 31, v9
	s_add_i32 s8, s8, s0
	s_lshl_b32 s1, s53, 7
	v_lshlrev_b32_e32 v3, 3, v2
	v_lshrrev_b32_e32 v8, 26, v8
	s_lshl_b32 s0, s8, 8
	s_and_b32 s1, s1, 0x80
	v_and_b32_e32 v3, 0x7ffff0, v3
	v_lshlrev_b32_e32 v7, 3, v6
	v_add_u32_e32 v10, v9, v8
	s_or_b32 s57, s0, s1
	v_add_u32_e32 v0, v4, v3
	v_lshlrev_b32_e32 v3, 5, v2
	s_movk_i32 s0, 0x1600
	v_and_b32_e32 v7, 0x7ffff0, v7
	v_ashrrev_i32_e32 v8, 6, v10
	v_and_b32_e32 v10, 0xc0, v10
	s_lshl_b32 s56, s11, 8
	v_and_b32_e32 v3, 32, v3
	v_ashrrev_i16_sdwa v5, v207, sext(v5) dst_sel:DWORD dst_unused:UNUSED_PAD src0_sel:DWORD src1_sel:BYTE_0
	v_mul_lo_u32 v0, v0, s0
	v_add_u32_e32 v11, v8, v7
	v_lshlrev_b32_e32 v7, 5, v6
	v_sub_u32_e32 v9, v9, v10
	s_mul_i32 s8, s57, 0x2c00
	v_add_u32_e32 v87, 0x10000, v85
	v_bfe_i32 v5, v5, 0, 16
	v_or_b32_e32 v0, v0, v3
	v_and_b32_e32 v7, 32, v7
	v_ashrrev_i16_sdwa v9, v207, sext(v9) dst_sel:DWORD dst_unused:UNUSED_PAD src0_sel:DWORD src1_sel:BYTE_0
	v_mul_lo_u32 v10, v11, s0
	s_mul_hi_i32 s1, s57, 0x2c00
	s_add_u32 s0, s16, s8
	v_readfirstlane_b32 s9, v87
	v_add_u32_e32 v88, 0x12000, v85
	v_add_lshl_u32 v0, v0, v5, 1
	v_bfe_i32 v9, v9, 0, 16
	v_or_b32_e32 v10, v10, v7
	s_addc_u32 s1, s17, s1
	s_mov_b32 m0, s9
	v_readfirstlane_b32 s9, v88
	s_mul_i32 s66, s11, 0x2c0000
	v_add_lshl_u32 v66, v10, v9, 1
	global_load_lds_dwordx4 v0, s[0:1]
	s_mov_b32 m0, s9
	s_mul_hi_i32 s72, s56, 0x2c00
	s_add_u32 s10, s20, s66
	v_readfirstlane_b32 s9, v85
	global_load_lds_dwordx4 v66, s[0:1]
	s_addc_u32 s11, s21, s72
	s_mov_b32 m0, s9
	v_readfirstlane_b32 s9, v86
	global_load_lds_dwordx4 v0, s[10:11]
	s_mov_b32 m0, s9
	s_add_i32 s9, s57, 0x80
	s_add_i32 s8, s8, 0x160000
	v_add_u32_e32 v89, 0x14000, v85
	s_mul_hi_i32 s9, s9, 0x2c00
	s_add_u32 s12, s16, s8
	v_readfirstlane_b32 s8, v89
	v_add_u32_e32 v90, 0x16000, v85
	global_load_lds_dwordx4 v66, s[10:11]
	s_addc_u32 s13, s17, s9
	s_mov_b32 m0, s8
	v_readfirstlane_b32 s8, v90
	global_load_lds_dwordx4 v0, s[12:13]
	s_mov_b32 m0, s8
	s_or_b32 s8, s56, 0x80
	s_mul_hi_i32 s9, s8, 0x2c00
	s_mulk_i32 s8, 0x2c00
	v_add_u32_e32 v91, 0x4000, v85
	s_add_u32 s8, s20, s8
	v_readfirstlane_b32 s14, v91
	v_add_u32_e32 v92, 0x6000, v85
	global_load_lds_dwordx4 v66, s[12:13]
	s_addc_u32 s9, s21, s9
	s_mov_b32 m0, s14
	v_readfirstlane_b32 s14, v92
	global_load_lds_dwordx4 v0, s[8:9]
	s_mov_b32 m0, s14
	v_ashrrev_i32_e32 v81, 8, v80
	global_load_lds_dwordx4 v66, s[8:9]
	v_cmp_eq_u32_e32 vcc, 1, v81
	s_and_saveexec_b64 s[14:15], vcc
	s_cbranch_execz .LBB0_688
	s_barrier
	s_setprio 1

.LBB0_758:
	v_mov_b32_e32 v140, v206
	s_barrier
	s_ashr_i32 s0, s52, 31
	v_ashrrev_i32_e32 v0, 31, v140
	v_lshrrev_b32_e32 v0, 26, v0
	v_add_u32_e32 v0, v140, v0
	v_ashrrev_i32_e32 v2, 6, v0
	v_bfe_i32 v0, v140, 27, 1
	v_lshlrev_b32_e32 v145, 4, v140
	v_lshrrev_b32_e32 v0, 22, v0
	s_lshr_b32 s0, s0, 29
	v_add_u32_e32 v0, v145, v0
	s_add_i32 s0, s52, s0
	v_and_b32_e32 v0, 0xfffffc00, v0
	s_ashr_i32 s1, s0, 3
	s_and_b32 s0, s0, -8
	v_sub_u32_e32 v0, v145, v0
	s_sub_i32 s0, s52, s0
	v_lshrrev_b32_e32 v3, 4, v0
	s_lshr_b32 s8, s0, 31
	v_bitop3_b32 v5, v3, v0, 32 bitop3:0x6c
	v_ashrrev_i32_e32 v0, 31, v0
	s_or_b32 s8, s8, 48
	v_lshrrev_b32_e32 v0, 26, v0
	s_mul_i32 s0, s8, s0
	v_add_u32_e32 v0, v5, v0
	s_add_i32 s0, s0, s1
	v_ashrrev_i32_e32 v4, 6, v0
	s_mul_hi_i32 s1, s0, 0x2aaaaaab
	v_mul_i32_i24_e32 v6, 64, v4
	v_add_u32_e32 v146, 0x2000, v145
	s_lshr_b32 s8, s1, 31
	s_ashr_i32 s1, s1, 5
	v_sub_u32_e32 v5, v5, v6
	v_ashrrev_i32_e32 v6, 31, v146
	s_add_i32 s1, s1, s8
	v_lshrrev_b32_e32 v6, 22, v6
	s_mul_i32 s8, s1, 0xc0
	v_add_u32_e32 v6, v146, v6
	s_sub_i32 s0, s0, s8
	v_ashrrev_i32_e32 v6, 10, v6
	s_sext_i32_i16 s8, s0
	v_mul_i32_i24_e32 v7, 0x400, v6
	s_bfe_u32 s8, s8, 0x2001d
	v_sub_u32_e32 v7, v146, v7
	s_add_i32 s8, s0, s8
	v_lshrrev_b32_e32 v8, 4, v7
	s_sext_i32_i16 s9, s8
	s_and_b32 s8, s8, 0xfffc
	v_bitop3_b32 v9, v8, v7, 32 bitop3:0x6c
	s_sub_i32 s0, s0, s8
	v_ashrrev_i32_e32 v8, 31, v9
	s_sext_i32_i16 s0, s0
	v_lshlrev_b32_e32 v3, 3, v2
	v_lshrrev_b32_e32 v8, 26, v8
	s_lshl_b32 s1, s1, 10
	s_lshl_b32 s56, s0, 8
	v_and_b32_e32 v3, 0x7ffff0, v3
	v_lshlrev_b32_e32 v7, 3, v6
	v_add_u32_e32 v10, v9, v8
	s_add_i32 s56, s56, s1
	v_add_u32_e32 v0, v4, v3
	v_lshlrev_b32_e32 v3, 5, v2
	s_movk_i32 s0, 0x1600
	v_and_b32_e32 v7, 0x7ffff0, v7
	v_ashrrev_i32_e32 v8, 6, v10
	s_ashr_i32 s53, s9, 2
	v_and_b32_e32 v3, 32, v3
	v_ashrrev_i16_sdwa v5, v207, sext(v5) dst_sel:DWORD dst_unused:UNUSED_PAD src0_sel:DWORD src1_sel:BYTE_0
	v_mul_lo_u32 v0, v0, s0
	v_add_u32_e32 v11, v8, v7
	v_and_b32_e32 v10, 0xc0, v10
	s_mul_i32 s57, s56, 0x2c00
	v_add_u32_e32 v149, 0x10000, v145
	v_bfe_i32 v5, v5, 0, 16
	v_or_b32_e32 v0, v0, v3
	v_sub_u32_e32 v9, v9, v10
	v_mul_lo_u32 v10, v11, s0
	s_mul_hi_i32 s54, s56, 0x2c00
	s_add_u32 s0, s16, s57
	v_readfirstlane_b32 s8, v149
	v_add_u32_e32 v150, 0x12000, v145
	v_add_lshl_u32 v0, v0, v5, 1
	s_addc_u32 s1, s17, s54
	s_mov_b32 m0, s8
	v_readfirstlane_b32 s8, v150
	v_lshlrev_b32_e32 v7, 5, v6
	global_load_lds_dwordx4 v0, s[0:1]
	s_mov_b32 m0, s8
	s_mul_i32 s8, s53, 0x160000
	v_and_b32_e32 v7, 32, v7
	v_ashrrev_i16_sdwa v9, v207, sext(v9) dst_sel:DWORD dst_unused:UNUSED_PAD src0_sel:DWORD src1_sel:BYTE_0
	s_ashr_i32 s9, s8, 31
	v_bfe_i32 v9, v9, 0, 16
	v_or_b32_e32 v10, v10, v7
	s_lshl_b64 s[10:11], s[8:9], 1
	v_add_lshl_u32 v130, v10, v9, 1
	s_add_u32 s8, s20, s10
	v_readfirstlane_b32 s12, v145
	global_load_lds_dwordx4 v130, s[0:1]
	s_addc_u32 s9, s21, s11
	s_mov_b32 m0, s12
	v_readfirstlane_b32 s12, v146
	global_load_lds_dwordx4 v0, s[8:9]
	s_mov_b32 m0, s12
	s_or_b32 s12, s56, 0x80
	s_mul_hi_i32 s13, s12, 0x2c00
	s_mulk_i32 s12, 0x2c00
	v_add_u32_e32 v151, 0x14000, v145
	s_add_u32 s12, s16, s12
	v_readfirstlane_b32 s14, v151
	v_add_u32_e32 v152, 0x16000, v145
	global_load_lds_dwordx4 v130, s[8:9]
	s_addc_u32 s13, s17, s13
	s_mov_b32 m0, s14
	v_readfirstlane_b32 s14, v152
	v_add_u32_e32 v153, 0x4000, v145
	global_load_lds_dwordx4 v0, s[12:13]
	s_mov_b32 m0, s14
	s_add_u32 s14, s8, 0x160000
	v_readfirstlane_b32 s62, v153
	v_add_u32_e32 v154, 0x6000, v145
	global_load_lds_dwordx4 v130, s[12:13]
	s_addc_u32 s15, s9, 0
	s_mov_b32 m0, s62
	v_readfirstlane_b32 s62, v154
	global_load_lds_dwordx4 v0, s[14:15]
	s_mov_b32 m0, s62
	v_ashrrev_i32_e32 v141, 8, v140
	global_load_lds_dwordx4 v130, s[14:15]
	v_cmp_eq_u32_e32 vcc, 1, v141
	s_and_saveexec_b64 s[14:15], vcc
	s_cbranch_execz .LBB0_760
	s_barrier
	s_setprio 1
